# P0 x-row bf16 stores marked sc1 (write-through) so the grid barrier's L2 write-back before P1 has almost nothing left to flush
# speedup vs baseline: 1.0025x; 1.0025x over previous
; #define GAS __attribute__((address_space(1)))
; __device__ __forceinline__ void rms_rows4_to_bf16(int lane, const float* x0, bf16* o0, size_t stride) {
;     ...
;     for (int r = 0; r < 4; ++r) { const GAS f32x4* xr = (const GAS f32x4*)(x0 + r * stride) + lane;
; #pragma unroll
;         for (int j = 0; j < 4; ++j) v[r][j] = __builtin_nontemporal_load(&xr[64 * j]); }
; #pragma unroll
;     for (int r = 0; r < 4; ++r) { float s = 0.f;
; #pragma unroll
;         for (int j = 0; j < 4; ++j) s += (v[r][j].x * v[r][j].x + v[r][j].y * v[r][j].y) + (v[r][j].z * v[r][j].z + v[r][j].w * v[r][j].w);
;         const float rs = rsqrtf(wave_sum(s) * (1.f / DM) + EPS);
; __device__ __forceinline__ void p0_prologue(Frame& F, const Ptrs& P) {
;     ...
;     for (;;) {
;         if (F.tid == 0) F.MISC[12] = __hip_atomic_fetch_add((unsigned*)(P.ws + WS_CTL) + CW_ROWQ, 1u, __ATOMIC_RELAXED, __HIP_MEMORY_SCOPE_AGENT);
;         __syncthreads();
;         const unsigned c = F.MISC[12];
;         __syncthreads();
;         if (c >= (unsigned)(MROWS / 32)) break;
;         const size_t m0 = (size_t)c * 32 + F.wave * 4;
;         rms_rows4_to_bf16(F.lane, P.x + m0 * DM, XB + m0 * DM, (size_t)DM);
.LBB0_68:
	s_or_b64 exec, exec, s[46:47]
	s_waitcnt lgkmcnt(0)
	s_barrier
	ds_read_b32 v2, v1
	s_mov_b64 s[46:47], -1
	s_waitcnt lgkmcnt(0)
	s_barrier
	v_cmp_lt_u32_e32 vcc, s56, v2
	v_readfirstlane_b32 s0, v2
	s_cbranch_vccnz .LBB0_63
	s_lshl_b32 s0, s0, 5
	s_add_i32 s0, s0, s33
	s_lshl_b64 s[46:47], s[0:1], 12
	s_add_u32 s46, s16, s46
	s_addc_u32 s47, s17, s47
	v_lshl_add_u64 v[18:19], s[46:47], 0, v[66:67]
	global_load_dwordx4 v[62:65], v66, s[46:47] nt
	global_load_dwordx4 v[58:61], v66, s[46:47] offset:1024 nt
	global_load_dwordx4 v[50:53], v66, s[46:47] offset:3072 nt
	global_load_dwordx4 v[54:57], v66, s[46:47] offset:2048 nt
	v_add_co_u32_e32 v2, vcc, s58, v18
	v_lshl_add_u64 v[4:5], v[18:19], 0, s[4:5]
	s_nop 0
	v_addc_co_u32_e32 v3, vcc, 0, v19, vcc
	global_load_dwordx4 v[46:49], v[2:3], off offset:-4096 nt
	global_load_dwordx4 v[42:45], v[4:5], off offset:1024 nt
	global_load_dwordx4 v[10:13], v[4:5], off offset:3072 nt
	global_load_dwordx4 v[14:17], v[4:5], off offset:2048 nt
	v_cmp_lt_i32_e32 vcc, v76, v75
	v_lshl_add_u64 v[20:21], v[18:19], 0, s[6:7]
	s_lshl_b64 s[46:47], s[0:1], 11
	v_cndmask_b32_e32 v4, v74, v76, vcc
	v_cmp_lt_i32_e32 vcc, v77, v75
	v_lshlrev_b32_e32 v84, 2, v4
	global_load_dwordx4 v[6:9], v[2:3], off nt
	s_nop 0
	global_load_dwordx4 v[2:5], v[20:21], off offset:1024 nt
	v_cndmask_b32_e32 v41, v74, v77, vcc
	v_lshlrev_b32_e32 v85, 2, v41
	v_cmp_lt_i32_e32 vcc, v78, v75
	s_add_u32 s46, s19, s46
	s_addc_u32 s47, s23, s47
	v_cndmask_b32_e32 v70, v74, v78, vcc
	v_lshlrev_b32_e32 v86, 2, v70
	v_cmp_lt_i32_e32 vcc, v79, v75
	s_waitcnt vmcnt(9)
	v_pk_mul_f32 v[22:23], v[64:65], v[64:65]
	v_pk_mul_f32 v[24:25], v[62:63], v[62:63]
	s_waitcnt vmcnt(8)
	v_pk_mul_f32 v[26:27], v[60:61], v[60:61]
	v_pk_mul_f32 v[28:29], v[58:59], v[58:59]
	s_waitcnt vmcnt(7)
	v_mul_f32_e32 v33, v52, v52
	s_waitcnt vmcnt(6)
	v_mul_f32_e32 v30, v55, v55
	v_mul_f32_e32 v32, v57, v57
	v_mul_f32_e32 v36, v53, v53
	v_pk_mov_b32 v[34:35], v[24:25], v[22:23] op_sel:[1,0]
	v_mov_b32_e32 v25, v23
	v_pk_mov_b32 v[22:23], v[28:29], v[26:27] op_sel:[1,0]
	v_mov_b32_e32 v29, v27
	v_pk_fma_f32 v[26:27], v[54:55], v[54:55], v[30:31] op_sel_hi:[1,1,0]
	v_pk_fma_f32 v[30:31], v[56:57], v[56:57], v[32:33] op_sel_hi:[1,1,0]
	v_pk_add_f32 v[24:25], v[34:35], v[24:25]
	v_pk_add_f32 v[22:23], v[22:23], v[28:29]
	v_mov_b32_e32 v27, v33
	v_mov_b32_e32 v31, v36
	s_waitcnt vmcnt(5)
	v_pk_mul_f32 v[28:29], v[48:49], v[48:49]
	v_pk_mul_f32 v[32:33], v[46:47], v[46:47]
	s_waitcnt vmcnt(4)
	v_pk_mul_f32 v[34:35], v[44:45], v[44:45]
	v_pk_mul_f32 v[36:37], v[42:43], v[42:43]
	v_mul_f32_e32 v69, v50, v50
	v_mul_f32_e32 v71, v51, v51
	v_pk_add_f32 v[24:25], v[24:25], v[24:25] op_sel:[0,1] op_sel_hi:[1,0]
	v_pk_add_f32 v[22:23], v[22:23], v[22:23] op_sel:[0,1] op_sel_hi:[1,0]
	v_pk_add_f32 v[26:27], v[26:27], v[30:31]
	v_pk_mov_b32 v[30:31], v[32:33], v[28:29] op_sel:[1,0]
	v_mov_b32_e32 v33, v29
	v_pk_mov_b32 v[28:29], v[36:37], v[34:35] op_sel:[1,0]
	v_mov_b32_e32 v37, v35
	s_waitcnt vmcnt(2)
	v_mul_f32_e32 v38, v15, v15
	v_mul_f32_e32 v40, v17, v17
	v_mov_b32_e32 v25, v69
	v_mov_b32_e32 v23, v71
	v_pk_add_f32 v[30:31], v[30:31], v[32:33]
	v_pk_add_f32 v[28:29], v[28:29], v[36:37]
	v_mul_f32_e32 v72, v10, v10
	v_mul_f32_e32 v73, v11, v11
	v_mul_f32_e32 v82, v12, v12
	v_mul_f32_e32 v83, v13, v13
	v_pk_fma_f32 v[34:35], v[14:15], v[14:15], v[38:39] op_sel_hi:[1,1,0]
	v_pk_fma_f32 v[38:39], v[16:17], v[16:17], v[40:41] op_sel_hi:[1,1,0]
	v_pk_add_f32 v[22:23], v[24:25], v[22:23]
	v_pk_add_f32 v[24:25], v[30:31], v[30:31] op_sel:[0,1] op_sel_hi:[1,0]
	v_pk_add_f32 v[28:29], v[28:29], v[28:29] op_sel:[0,1] op_sel_hi:[1,0]
	v_mov_b32_e32 v35, v82
	v_mov_b32_e32 v39, v83
	v_mov_b32_e32 v25, v72
	v_mov_b32_e32 v29, v73
	v_pk_add_f32 v[30:31], v[34:35], v[38:39]
	v_pk_add_f32 v[24:25], v[24:25], v[28:29]
	v_pk_add_f32 v[22:23], v[22:23], v[26:27]
	v_pk_add_f32 v[24:25], v[24:25], v[30:31]
	v_mov_b32_e32 v27, v22
	v_mov_b32_e32 v26, v24
	v_mov_b32_e32 v22, v25
	v_pk_add_f32 v[22:23], v[26:27], v[22:23]
	ds_bpermute_b32 v25, v84, v23
	ds_bpermute_b32 v24, v84, v22
	v_cndmask_b32_e32 v26, v74, v79, vcc
	v_lshlrev_b32_e32 v87, 2, v26
	v_cmp_lt_i32_e32 vcc, v80, v75
	v_lshl_add_u64 v[70:71], v[18:19], 0, s[8:9]
	s_waitcnt lgkmcnt(0)
	v_pk_add_f32 v[22:23], v[22:23], v[24:25]
	ds_bpermute_b32 v25, v85, v23
	ds_bpermute_b32 v24, v85, v22
	v_cndmask_b32_e32 v27, v74, v80, vcc
	v_lshlrev_b32_e32 v88, 2, v27
	v_cmp_lt_i32_e32 vcc, v81, v75
	v_mov_b64_e32 v[72:73], s[22:23]
	s_waitcnt lgkmcnt(0)
	v_pk_add_f32 v[22:23], v[22:23], v[24:25]
	ds_bpermute_b32 v25, v86, v23
	ds_bpermute_b32 v24, v86, v22
	v_cndmask_b32_e32 v28, v74, v81, vcc
	v_lshlrev_b32_e32 v89, 2, v28
	v_add_co_u32_e32 v18, vcc, s59, v18
	s_waitcnt lgkmcnt(0)
	v_pk_add_f32 v[22:23], v[22:23], v[24:25]
	ds_bpermute_b32 v25, v87, v23
	ds_bpermute_b32 v24, v87, v22
	v_addc_co_u32_e32 v19, vcc, 0, v19, vcc
	v_mov_b32_e32 v69, v67
	s_waitcnt lgkmcnt(0)
	v_pk_add_f32 v[22:23], v[22:23], v[24:25]
	ds_bpermute_b32 v25, v88, v23
	ds_bpermute_b32 v24, v88, v22
	s_waitcnt lgkmcnt(0)
	v_pk_add_f32 v[30:31], v[22:23], v[24:25]
	ds_bpermute_b32 v33, v89, v31
	ds_bpermute_b32 v32, v89, v30
	global_load_dwordx4 v[38:41], v[20:21], off offset:2048 nt
	global_load_dwordx4 v[34:37], v[20:21], off offset:3072 nt
	global_load_dwordx4 v[26:29], v[70:71], off offset:1024 nt
	global_load_dwordx4 v[22:25], v[70:71], off offset:2048 nt
	s_waitcnt lgkmcnt(0)
; #define GAS __attribute__((address_space(1)))
; __device__ __forceinline__ unsigned pk2(float lo, float hi) { return f2bf(lo) | (f2bf(hi) << 16); }
; __device__ __forceinline__ void rms_rows4_to_bf16(int lane, const float* x0, bf16* o0, size_t stride) {
;     ...
;     for (int r = 0; r < 4; ++r) { float s = 0.f;
; #pragma unroll
;         for (int j = 0; j < 4; ++j) s += (v[r][j].x * v[r][j].x + v[r][j].y * v[r][j].y) + (v[r][j].z * v[r][j].z + v[r][j].w * v[r][j].w);
;         const float rs = rsqrtf(wave_sum(s) * (1.f / DM) + EPS);
;         GAS unsigned long long* o8 = (GAS unsigned long long*)(o0 + r * stride) + lane;
; #pragma unroll
;         for (int j = 0; j < 4; ++j) o8[64 * j] = (unsigned long long)pk2(v[r][j].x * rs, v[r][j].y * rs) | ((unsigned long long)pk2(v[r][j].z * rs, v[r][j].w * rs) << 32); }
	v_pk_add_f32 v[20:21], v[30:31], v[32:33]
	s_nop 0
	v_pk_fma_f32 v[82:83], v[20:21], s[18:19], v[72:73] op_sel_hi:[1,0,0]
	s_nop 0
	v_mul_f32_e32 v20, 0x4b800000, v83
	v_cmp_gt_f32_e32 vcc, s62, v83
	s_nop 1
	v_cndmask_b32_e32 v20, v83, v20, vcc
	v_rsq_f32_e32 v83, v20
	global_load_dwordx4 v[30:33], v[18:19], off nt
	s_nop 0
	global_load_dwordx4 v[18:21], v[70:71], off offset:3072 nt
	v_lshl_add_u64 v[70:71], s[46:47], 0, v[68:69]
	v_mul_f32_e32 v69, 0x45800000, v83
	v_cndmask_b32_e32 v69, v83, v69, vcc
	v_mul_f32_e32 v62, v62, v69
	v_mul_f32_e32 v63, v63, v69
	v_bfe_u32 v83, v62, 16, 1
	v_add3_u32 v62, v62, v83, s63
	v_bfe_u32 v83, v63, 16, 1
	v_lshrrev_b32_e32 v62, 16, v62
	v_add3_u32 v63, v63, v83, s63
	v_and_or_b32 v62, v63, s64, v62
	v_mul_f32_e32 v63, v64, v69
	v_mul_f32_e32 v64, v65, v69
	v_bfe_u32 v65, v63, 16, 1
	v_add3_u32 v63, v63, v65, s63
	v_bfe_u32 v65, v64, 16, 1
	v_lshrrev_b32_e32 v63, 16, v63
	v_add3_u32 v64, v64, v65, s63
	v_and_or_b32 v63, v64, s64, v63
	v_mul_f32_e32 v58, v58, v69
	global_store_dwordx2 v68, v[62:63], s[46:47] sc1
	v_mul_f32_e32 v59, v59, v69
	v_bfe_u32 v62, v58, 16, 1
	v_add3_u32 v58, v58, v62, s63
	v_bfe_u32 v62, v59, 16, 1
	v_lshrrev_b32_e32 v58, 16, v58
	v_add3_u32 v59, v59, v62, s63
	v_and_or_b32 v58, v59, s64, v58
	v_mul_f32_e32 v59, v60, v69
	v_mul_f32_e32 v60, v61, v69
	v_bfe_u32 v61, v59, 16, 1
	v_add3_u32 v59, v59, v61, s63
	v_bfe_u32 v61, v60, 16, 1
	v_lshrrev_b32_e32 v59, 16, v59
	v_add3_u32 v60, v60, v61, s63
	v_and_or_b32 v59, v60, s64, v59
	v_mul_f32_e32 v54, v54, v69
	global_store_dwordx2 v68, v[58:59], s[46:47] offset:512 sc1
	v_mul_f32_e32 v55, v55, v69
	v_bfe_u32 v58, v54, 16, 1
	v_add3_u32 v54, v54, v58, s63
	v_bfe_u32 v58, v55, 16, 1
	v_lshrrev_b32_e32 v54, 16, v54
	v_add3_u32 v55, v55, v58, s63
	v_and_or_b32 v54, v55, s64, v54
	v_mul_f32_e32 v55, v56, v69
	v_mul_f32_e32 v56, v57, v69
	v_bfe_u32 v57, v55, 16, 1
	v_add3_u32 v55, v55, v57, s63
	v_bfe_u32 v57, v56, 16, 1
	v_lshrrev_b32_e32 v55, 16, v55
	v_add3_u32 v56, v56, v57, s63
	v_and_or_b32 v55, v56, s64, v55
	v_mul_f32_e32 v50, v50, v69
	global_store_dwordx2 v68, v[54:55], s[46:47] offset:1024 sc1
	v_mul_f32_e32 v51, v51, v69
	v_bfe_u32 v54, v50, 16, 1
	v_add3_u32 v50, v50, v54, s63
	v_bfe_u32 v54, v51, 16, 1
	v_lshrrev_b32_e32 v50, 16, v50
	v_add3_u32 v51, v51, v54, s63
	v_mul_f32_e32 v54, 0x4b800000, v82
	v_cmp_gt_f32_e32 vcc, s62, v82
	v_and_or_b32 v50, v51, s64, v50
	v_mul_f32_e32 v51, v52, v69
	v_cndmask_b32_e32 v54, v82, v54, vcc
	v_mul_f32_e32 v52, v53, v69
	v_bfe_u32 v53, v51, 16, 1
	v_rsq_f32_e32 v54, v54
	v_add3_u32 v51, v51, v53, s63
	v_bfe_u32 v53, v52, 16, 1
	v_lshrrev_b32_e32 v51, 16, v51
	v_add3_u32 v52, v52, v53, s63
	v_and_or_b32 v51, v52, s64, v51
	global_store_dwordx2 v68, v[50:51], s[46:47] offset:1536 sc1
	v_mul_f32_e32 v50, 0x45800000, v54
	v_cndmask_b32_e32 v52, v54, v50, vcc
	v_mul_f32_e32 v46, v46, v52
	v_mul_f32_e32 v47, v47, v52
	v_bfe_u32 v50, v46, 16, 1
	v_add3_u32 v46, v46, v50, s63
	v_bfe_u32 v50, v47, 16, 1
	v_lshrrev_b32_e32 v46, 16, v46
	v_add3_u32 v47, v47, v50, s63
	v_and_or_b32 v46, v47, s64, v46
	v_mul_f32_e32 v47, v48, v52
	v_mul_f32_e32 v48, v49, v52
	v_bfe_u32 v49, v47, 16, 1
	v_add3_u32 v47, v47, v49, s63
	v_bfe_u32 v49, v48, 16, 1
	v_lshrrev_b32_e32 v47, 16, v47
	v_add3_u32 v48, v48, v49, s63
	v_and_or_b32 v47, v48, s64, v47
	v_mul_f32_e32 v42, v42, v52
	global_store_dwordx2 v68, v[46:47], s[46:47] offset:2048 sc1
	v_mul_f32_e32 v43, v43, v52
	v_bfe_u32 v46, v42, 16, 1
	v_add3_u32 v42, v42, v46, s63
	v_bfe_u32 v46, v43, 16, 1
	v_lshrrev_b32_e32 v42, 16, v42
	v_add3_u32 v43, v43, v46, s63
	v_and_or_b32 v42, v43, s64, v42
	v_mul_f32_e32 v43, v44, v52
	v_mul_f32_e32 v44, v45, v52
	v_bfe_u32 v45, v43, 16, 1
	v_add3_u32 v43, v43, v45, s63
	v_bfe_u32 v45, v44, 16, 1
	v_lshrrev_b32_e32 v43, 16, v43
	v_add3_u32 v44, v44, v45, s63
	v_and_or_b32 v43, v44, s64, v43
	v_mul_f32_e32 v14, v14, v52
	global_store_dwordx2 v68, v[42:43], s[46:47] offset:2560 sc1
	v_mul_f32_e32 v15, v15, v52
	v_bfe_u32 v42, v14, 16, 1
	v_add3_u32 v14, v14, v42, s63
	v_bfe_u32 v42, v15, 16, 1
	v_add3_u32 v15, v15, v42, s63
	s_waitcnt vmcnt(13)
	v_pk_mul_f32 v[42:43], v[8:9], v[8:9]
	v_pk_mul_f32 v[44:45], v[6:7], v[6:7]
	v_lshrrev_b32_e32 v14, 16, v14
	v_pk_mov_b32 v[46:47], v[44:45], v[42:43] op_sel:[1,0]
	v_mov_b32_e32 v45, v43
	v_pk_add_f32 v[42:43], v[46:47], v[44:45]
	s_waitcnt vmcnt(12)
	v_pk_mul_f32 v[44:45], v[4:5], v[4:5]
	v_pk_mul_f32 v[46:47], v[2:3], v[2:3]
	v_and_or_b32 v14, v15, s64, v14
	v_pk_mov_b32 v[48:49], v[46:47], v[44:45] op_sel:[1,0]
	v_mov_b32_e32 v47, v45
	v_pk_add_f32 v[44:45], v[48:49], v[46:47]
	s_waitcnt vmcnt(10)
	v_mul_f32_e32 v15, v34, v34
	v_mul_f32_e32 v46, v35, v35
	v_pk_add_f32 v[42:43], v[42:43], v[42:43] op_sel:[0,1] op_sel_hi:[1,0]
	v_pk_add_f32 v[44:45], v[44:45], v[44:45] op_sel:[0,1] op_sel_hi:[1,0]
	v_mov_b32_e32 v43, v15
	v_mov_b32_e32 v45, v46
	v_pk_add_f32 v[42:43], v[42:43], v[44:45]
	v_mul_f32_e32 v44, v39, v39
	v_mul_f32_e32 v47, v36, v36
	v_pk_fma_f32 v[44:45], v[38:39], v[38:39], v[44:45] op_sel_hi:[1,1,0]
	v_mul_f32_e32 v46, v41, v41
	v_mul_f32_e32 v48, v37, v37
	v_mov_b32_e32 v45, v47
	v_pk_fma_f32 v[46:47], v[40:41], v[40:41], v[46:47] op_sel_hi:[1,1,0]
	s_waitcnt vmcnt(6)
; #define GAS __attribute__((address_space(1)))
; __device__ __forceinline__ unsigned pk2(float lo, float hi) { return f2bf(lo) | (f2bf(hi) << 16); }
; __device__ __forceinline__ void rms_rows4_to_bf16(int lane, const float* x0, bf16* o0, size_t stride) {
;     ...
;     for (int r = 0; r < 4; ++r) { float s = 0.f;
; #pragma unroll
;         for (int j = 0; j < 4; ++j) s += (v[r][j].x * v[r][j].x + v[r][j].y * v[r][j].y) + (v[r][j].z * v[r][j].z + v[r][j].w * v[r][j].w);
;         const float rs = rsqrtf(wave_sum(s) * (1.f / DM) + EPS);
;         GAS unsigned long long* o8 = (GAS unsigned long long*)(o0 + r * stride) + lane;
; #pragma unroll
;         for (int j = 0; j < 4; ++j) o8[64 * j] = (unsigned long long)pk2(v[r][j].x * rs, v[r][j].y * rs) | ((unsigned long long)pk2(v[r][j].z * rs, v[r][j].w * rs) << 32); }
	v_mul_f32_e32 v15, v18, v18
	v_mov_b32_e32 v47, v48
	v_pk_add_f32 v[44:45], v[44:45], v[46:47]
	v_pk_mul_f32 v[46:47], v[30:31], v[30:31]
	v_pk_add_f32 v[42:43], v[42:43], v[44:45]
	v_pk_mul_f32 v[44:45], v[32:33], v[32:33]
	s_nop 0
	v_pk_mov_b32 v[48:49], v[46:47], v[44:45] op_sel:[1,0]
	v_mov_b32_e32 v47, v45
	v_pk_add_f32 v[44:45], v[48:49], v[46:47]
	v_pk_mul_f32 v[46:47], v[28:29], v[28:29]
	v_pk_mul_f32 v[48:49], v[26:27], v[26:27]
	v_pk_add_f32 v[44:45], v[44:45], v[44:45] op_sel:[0,1] op_sel_hi:[1,0]
	v_pk_mov_b32 v[50:51], v[48:49], v[46:47] op_sel:[1,0]
	v_mov_b32_e32 v49, v47
	v_pk_add_f32 v[46:47], v[50:51], v[48:49]
	v_mul_f32_e32 v48, v19, v19
	v_pk_add_f32 v[46:47], v[46:47], v[46:47] op_sel:[0,1] op_sel_hi:[1,0]
	v_mov_b32_e32 v45, v15
	v_mov_b32_e32 v47, v48
	v_pk_add_f32 v[44:45], v[44:45], v[46:47]
	v_mul_f32_e32 v46, v23, v23
	v_mul_f32_e32 v49, v20, v20
	v_pk_fma_f32 v[46:47], v[22:23], v[22:23], v[46:47] op_sel_hi:[1,1,0]
	v_mul_f32_e32 v48, v25, v25
	v_mul_f32_e32 v50, v21, v21
	v_mov_b32_e32 v47, v49
	v_pk_fma_f32 v[48:49], v[24:25], v[24:25], v[48:49] op_sel_hi:[1,1,0]
	v_mul_f32_e32 v15, v16, v52
	v_mov_b32_e32 v49, v50
	v_pk_add_f32 v[46:47], v[46:47], v[48:49]
	v_bfe_u32 v16, v15, 16, 1
	v_pk_add_f32 v[44:45], v[44:45], v[46:47]
	v_mov_b32_e32 v47, v42
	v_mov_b32_e32 v46, v44
	v_mov_b32_e32 v42, v45
	v_pk_add_f32 v[42:43], v[46:47], v[42:43]
	ds_bpermute_b32 v45, v84, v43
	ds_bpermute_b32 v44, v84, v42
	v_mul_f32_e32 v46, v17, v52
	v_add3_u32 v15, v15, v16, s63
	v_lshrrev_b32_e32 v15, 16, v15
	s_waitcnt lgkmcnt(0)
	v_pk_add_f32 v[16:17], v[42:43], v[44:45]
	ds_bpermute_b32 v43, v85, v17
	ds_bpermute_b32 v42, v85, v16
	v_bfe_u32 v44, v46, 16, 1
	v_add3_u32 v44, v46, v44, s63
	v_and_or_b32 v15, v44, s64, v15
	v_mul_f32_e32 v44, v10, v52
	s_waitcnt lgkmcnt(0)
	v_pk_add_f32 v[16:17], v[16:17], v[42:43]
	ds_bpermute_b32 v43, v86, v17
	ds_bpermute_b32 v42, v86, v16
	v_mul_f32_e32 v45, v11, v52
	global_store_dwordx2 v68, v[14:15], s[46:47] offset:3072 sc1
	v_bfe_u32 v46, v44, 16, 1
	s_waitcnt lgkmcnt(0)
	v_pk_add_f32 v[10:11], v[16:17], v[42:43]
	ds_bpermute_b32 v15, v87, v11
	ds_bpermute_b32 v14, v87, v10
	v_add3_u32 v16, v44, v46, s63
	v_bfe_u32 v17, v45, 16, 1
	v_lshrrev_b32_e32 v16, 16, v16
	v_add3_u32 v17, v45, v17, s63
	s_waitcnt lgkmcnt(0)
	v_pk_add_f32 v[10:11], v[10:11], v[14:15]
	ds_bpermute_b32 v15, v88, v11
	ds_bpermute_b32 v14, v88, v10
	v_and_or_b32 v16, v17, s64, v16
	v_mul_f32_e32 v17, v12, v52
	v_mul_f32_e32 v42, v13, v52
	v_bfe_u32 v43, v17, 16, 1
	s_waitcnt lgkmcnt(0)
	v_pk_add_f32 v[10:11], v[10:11], v[14:15]
	ds_bpermute_b32 v13, v89, v11
	ds_bpermute_b32 v12, v89, v10
	v_add3_u32 v14, v17, v43, s63
	v_bfe_u32 v15, v42, 16, 1
	v_lshrrev_b32_e32 v14, 16, v14
	v_add3_u32 v15, v42, v15, s63
	s_waitcnt lgkmcnt(0)
; #define GAS __attribute__((address_space(1)))
; __device__ __forceinline__ unsigned pk2(float lo, float hi) { return f2bf(lo) | (f2bf(hi) << 16); }
; __device__ __forceinline__ void rms_rows4_to_bf16(int lane, const float* x0, bf16* o0, size_t stride) {
;     ...
;     for (int r = 0; r < 4; ++r) { float s = 0.f;
; #pragma unroll
;         for (int j = 0; j < 4; ++j) s += (v[r][j].x * v[r][j].x + v[r][j].y * v[r][j].y) + (v[r][j].z * v[r][j].z + v[r][j].w * v[r][j].w);
;         const float rs = rsqrtf(wave_sum(s) * (1.f / DM) + EPS);
;         GAS unsigned long long* o8 = (GAS unsigned long long*)(o0 + r * stride) + lane;
; #pragma unroll
;         for (int j = 0; j < 4; ++j) o8[64 * j] = (unsigned long long)pk2(v[r][j].x * rs, v[r][j].y * rs) | ((unsigned long long)pk2(v[r][j].z * rs, v[r][j].w * rs) << 32); }
; __device__ __forceinline__ void p0_prologue(Frame& F, const Ptrs& P) {
;     ...
;     for (;;) {
;         if (F.tid == 0) F.MISC[12] = __hip_atomic_fetch_add((unsigned*)(P.ws + WS_CTL) + CW_ROWQ, 1u, __ATOMIC_RELAXED, __HIP_MEMORY_SCOPE_AGENT);
;         __syncthreads();
;         const unsigned c = F.MISC[12];
;         __syncthreads();
;         if (c >= (unsigned)(MROWS / 32)) break;
;         const size_t m0 = (size_t)c * 32 + F.wave * 4;
;         rms_rows4_to_bf16(F.lane, P.x + m0 * DM, XB + m0 * DM, (size_t)DM);
	v_pk_add_f32 v[10:11], v[10:11], v[12:13]
	v_and_or_b32 v17, v15, s64, v14
	v_pk_fma_f32 v[10:11], v[10:11], s[18:19], v[72:73] op_sel_hi:[1,0,0]
	global_store_dwordx2 v68, v[16:17], s[46:47] offset:3584 sc1
	v_mul_f32_e32 v12, 0x4b800000, v11
	v_cmp_gt_f32_e32 vcc, s62, v11
	s_mov_b64 s[46:47], 0
	s_nop 0
	v_cndmask_b32_e32 v11, v11, v12, vcc
	v_rsq_f32_e32 v11, v11
	v_lshl_add_u64 v[12:13], v[70:71], 0, s[4:5]
	v_mul_f32_e32 v14, 0x45800000, v11
	v_cndmask_b32_e32 v11, v11, v14, vcc
	v_mul_f32_e32 v6, v6, v11
	v_mul_f32_e32 v7, v7, v11
	v_bfe_u32 v14, v6, 16, 1
	v_add3_u32 v6, v6, v14, s63
	v_bfe_u32 v14, v7, 16, 1
	v_lshrrev_b32_e32 v6, 16, v6
	v_add3_u32 v7, v7, v14, s63
	v_and_or_b32 v6, v7, s64, v6
	v_mul_f32_e32 v7, v8, v11
	v_mul_f32_e32 v8, v9, v11
	v_bfe_u32 v9, v7, 16, 1
	v_add3_u32 v7, v7, v9, s63
	v_bfe_u32 v9, v8, 16, 1
	v_lshrrev_b32_e32 v7, 16, v7
	v_add3_u32 v8, v8, v9, s63
	v_and_or_b32 v7, v8, s64, v7
	v_add_co_u32_e32 v8, vcc, s57, v70
	v_mul_f32_e32 v2, v2, v11
	s_nop 0
	v_addc_co_u32_e32 v9, vcc, 0, v71, vcc
	global_store_dwordx2 v[8:9], v[6:7], off sc1
	v_mul_f32_e32 v3, v3, v11
	v_bfe_u32 v6, v2, 16, 1
	v_add3_u32 v2, v2, v6, s63
	v_bfe_u32 v6, v3, 16, 1
	v_lshrrev_b32_e32 v2, 16, v2
	v_add3_u32 v3, v3, v6, s63
	v_and_or_b32 v2, v3, s64, v2
	v_mul_f32_e32 v3, v4, v11
	v_mul_f32_e32 v4, v5, v11
	v_bfe_u32 v5, v3, 16, 1
	v_add3_u32 v3, v3, v5, s63
	v_bfe_u32 v5, v4, 16, 1
	v_lshrrev_b32_e32 v3, 16, v3
	v_add3_u32 v4, v4, v5, s63
	v_and_or_b32 v3, v4, s64, v3
	global_store_dwordx2 v[12:13], v[2:3], off offset:512 sc1
	v_mul_f32_e32 v2, v38, v11
	v_mul_f32_e32 v3, v39, v11
	v_bfe_u32 v4, v2, 16, 1
	v_add3_u32 v2, v2, v4, s63
	v_bfe_u32 v4, v3, 16, 1
	v_lshrrev_b32_e32 v2, 16, v2
	v_add3_u32 v3, v3, v4, s63
	v_and_or_b32 v2, v3, s64, v2
	v_mul_f32_e32 v3, v40, v11
	v_mul_f32_e32 v4, v41, v11
	v_bfe_u32 v5, v3, 16, 1
	v_add3_u32 v3, v3, v5, s63
	v_bfe_u32 v5, v4, 16, 1
	v_lshrrev_b32_e32 v3, 16, v3
	v_add3_u32 v4, v4, v5, s63
	v_and_or_b32 v3, v4, s64, v3
	global_store_dwordx2 v[12:13], v[2:3], off offset:1024 sc1
	v_mul_f32_e32 v2, v34, v11
	v_mul_f32_e32 v3, v35, v11
	v_bfe_u32 v4, v2, 16, 1
	v_add3_u32 v2, v2, v4, s63
	v_bfe_u32 v4, v3, 16, 1
	v_lshrrev_b32_e32 v2, 16, v2
	v_add3_u32 v3, v3, v4, s63
	v_mul_f32_e32 v6, 0x4b800000, v10
	v_cmp_gt_f32_e32 vcc, s62, v10
	v_and_or_b32 v2, v3, s64, v2
	v_mul_f32_e32 v3, v36, v11
	v_cndmask_b32_e32 v6, v10, v6, vcc
	v_mul_f32_e32 v4, v37, v11
	v_bfe_u32 v5, v3, 16, 1
	v_rsq_f32_e32 v6, v6
	v_add3_u32 v3, v3, v5, s63
	v_bfe_u32 v5, v4, 16, 1
	v_lshrrev_b32_e32 v3, 16, v3
	v_add3_u32 v4, v4, v5, s63
	v_and_or_b32 v3, v4, s64, v3
	global_store_dwordx2 v[12:13], v[2:3], off offset:1536 sc1
	v_mul_f32_e32 v2, 0x45800000, v6
	v_cndmask_b32_e32 v6, v6, v2, vcc
	v_mul_f32_e32 v4, v30, v6
	v_mul_f32_e32 v5, v31, v6
	v_bfe_u32 v7, v4, 16, 1
	v_add3_u32 v4, v4, v7, s63
	v_bfe_u32 v7, v5, 16, 1
	v_lshrrev_b32_e32 v4, 16, v4
	v_add3_u32 v5, v5, v7, s63
	v_and_or_b32 v4, v5, s64, v4
	v_mul_f32_e32 v5, v32, v6
	v_mul_f32_e32 v7, v33, v6
	v_bfe_u32 v10, v5, 16, 1
	v_add3_u32 v5, v5, v10, s63
	v_bfe_u32 v10, v7, 16, 1
	v_lshrrev_b32_e32 v5, 16, v5
	v_add3_u32 v7, v7, v10, s63
	v_and_or_b32 v5, v7, s64, v5
	global_store_dwordx2 v[8:9], v[4:5], off offset:2048 sc1
	v_mul_f32_e32 v4, v26, v6
	v_mul_f32_e32 v5, v27, v6
	v_bfe_u32 v7, v4, 16, 1
	v_add3_u32 v4, v4, v7, s63
	v_bfe_u32 v7, v5, 16, 1
	v_lshrrev_b32_e32 v4, 16, v4
	v_add3_u32 v5, v5, v7, s63
	v_and_or_b32 v4, v5, s64, v4
	v_mul_f32_e32 v5, v28, v6
	v_mul_f32_e32 v7, v29, v6
	v_bfe_u32 v8, v5, 16, 1
	v_add3_u32 v5, v5, v8, s63
	v_bfe_u32 v8, v7, 16, 1
	v_lshrrev_b32_e32 v5, 16, v5
	v_add3_u32 v7, v7, v8, s63
	v_lshl_add_u64 v[2:3], v[70:71], 0, s[24:25]
	v_and_or_b32 v5, v7, s64, v5
	global_store_dwordx2 v[2:3], v[4:5], off offset:512 sc1
	v_mul_f32_e32 v4, v22, v6
	v_mul_f32_e32 v5, v23, v6
	v_bfe_u32 v7, v4, 16, 1
	v_add3_u32 v4, v4, v7, s63
	v_bfe_u32 v7, v5, 16, 1
	v_lshrrev_b32_e32 v4, 16, v4
	v_add3_u32 v5, v5, v7, s63
	v_and_or_b32 v4, v5, s64, v4
	v_mul_f32_e32 v5, v24, v6
	v_mul_f32_e32 v7, v25, v6
	v_bfe_u32 v8, v5, 16, 1
	v_add3_u32 v5, v5, v8, s63
	v_bfe_u32 v8, v7, 16, 1
	v_lshrrev_b32_e32 v5, 16, v5
	v_add3_u32 v7, v7, v8, s63
	v_and_or_b32 v5, v7, s64, v5
	global_store_dwordx2 v[2:3], v[4:5], off offset:1024 sc1
	v_mul_f32_e32 v4, v18, v6
	v_mul_f32_e32 v5, v19, v6
	v_bfe_u32 v7, v4, 16, 1
	v_add3_u32 v4, v4, v7, s63
	v_bfe_u32 v7, v5, 16, 1
	v_lshrrev_b32_e32 v4, 16, v4
	v_add3_u32 v5, v5, v7, s63
	v_and_or_b32 v4, v5, s64, v4
	v_mul_f32_e32 v5, v20, v6
	v_mul_f32_e32 v6, v21, v6
	v_bfe_u32 v7, v5, 16, 1
	v_add3_u32 v5, v5, v7, s63
	v_bfe_u32 v7, v6, 16, 1
	v_lshrrev_b32_e32 v5, 16, v5
	v_add3_u32 v6, v6, v7, s63
	v_and_or_b32 v5, v6, s64, v5
	global_store_dwordx2 v[2:3], v[4:5], off offset:1536 sc1
	s_branch .LBB0_63
